# v50 + up0 block-1 conv-weight loads at the epilogue top + P7 gate ss loads one row group ahead + P15 loads up front (all three individually neutral)
# baseline (speedup 1.0000x reference)
; #define PG8_LAS __attribute__((address_space(3)))
; __device__ __forceinline__ void st16_wt(void* p, f32x4 v) { asm volatile("global_store_dwordx4 %0, %1, off sc1\n\ts_nop 1" :: "v"(p), "v"(v) : "memory"); }
; __device__ __forceinline__ float rstd_of(float ss) { return __builtin_amdgcn_rsqf(ss * (1.0f / 2048.0f) + NORM_EPS); }
;     __device__ __forceinline__ void operator()(const f32x4 (&acc)[2][2][4][2], const Unit& u, int wr, int wc, int fr, int fq) const {
;     ...
;         float rs[2][4];
; #pragma unroll
;         for (int ai = 0; ai < 2; ++ai)
; #pragma unroll
;             for (int m = 0; m < 4; ++m) rs[ai][m] = rstd_of(ss[u.pm * BM + ai * HALF + wr * 64 + 4 * fr + m]);
;         if (fr == 15) {
; #pragma unroll
;             for (int ai = 0; ai < 2; ++ai) { const int blk = 2 * ai + wr;
; #pragma unroll
;                 for (int n = 0; n < 2; ++n) { *(PG8_LAS f32x4*)(xch + ((blk * 2 + 0) * 4 + wc) * 32 + 8 * fq + 4 * n) = acc[ai][0][2][n] * rs[ai][2]; *(PG8_LAS f32x4*)(xch + ((blk * 2 + 1) * 4 + wc) * 32 + 8 * fq + 4 * n) = acc[ai][0][3][n] * rs[ai][3]; } }
;             if (wr == 1) {
; #pragma unroll
;                 for (int n = 0; n < 2; ++n) { st16_wt(HALO + ((size_t)u.pm * 2 + 0) * DFFC + col + 4 * n, acc[1][0][2][n] * rs[1][2]); st16_wt(HALO + ((size_t)u.pm * 2 + 1) * DFFC + col + 4 * n, acc[1][0][3][n] * rs[1][3]); } }
;         }
;         asm volatile("s_waitcnt lgkmcnt(0)" ::: "memory"); __builtin_amdgcn_s_barrier(); asm volatile("" ::: "memory");
;         const bool prompt = u.pm < PROMPT_TILES;
; #pragma unroll
;         for (int ai = 0; ai < 2; ++ai) { const int blk = 2 * ai + wr; const bool pend = prompt && blk == 0 && (u.pm & 15) != 0;
;             const int sb = (u.pm - PROMPT_TILES) * 4 + blk;
;             u32x2 pk[4][2];
; #pragma unroll
;             for (int n = 0; n < 2; ++n) { const int c = col + 4 * n;
;                 const f32x4 w0 = *(const f32x4*)(cw + c), w1 = *(const f32x4*)(cw + DFFC + c), w2 = *(const f32x4*)(cw + 2 * DFFC + c), bb = *(const f32x4*)(cb + c);
;                 f32x4 h2, h3;
;                 if (!prompt) { h2 = *(const f32x4*)(state + ((size_t)sb * 2 + 0) * DFFC + c); h3 = *(const f32x4*)(state + ((size_t)sb * 2 + 1) * DFFC + c); }
.LBB0_399:
	v_lshl_add_u32 v128, s52, 8, v192
	v_ashrrev_i32_e32 v129, 31, v128
	v_lshl_add_u64 v[130:131], v[128:129], 2, s[66:67]
	v_add_u32_e32 v128, 0x80, v128
	global_load_dwordx4 v[160:163], v[130:131], off
	v_ashrrev_i32_e32 v129, 31, v128
	v_lshl_add_u64 v[128:129], v[128:129], 2, s[66:67]
	global_load_dwordx4 v[128:131], v[128:129], off
	v_readlane_b32 s0, v249, 5
	v_readlane_b32 s1, v249, 6
	v_lshl_add_u32 v198, s4, 7, v231
	v_readlane_b32 s38, v250, 27
	v_readlane_b32 s39, v250, 28
	v_readlane_b32 s40, v250, 29
	v_readlane_b32 s41, v250, 30
	v_mov_b32_e32 v208, v198
	v_ashrrev_i32_e32 v209, 31, v198
	v_lshlrev_b64 v[208:209], 2, v[208:209]
	v_lshl_add_u64 v[246:247], s[38:39], 0, v[208:209]
	global_load_dwordx4 v[218:221], v[246:247], off
	v_lshl_add_u64 v[246:247], s[94:95], 0, v[208:209]
	global_load_dwordx4 v[222:225], v[246:247], off
	v_lshl_add_u64 v[246:247], s[96:97], 0, v[208:209]
	global_load_dwordx4 v[226:229], v[246:247], off
	v_lshl_add_u64 v[246:247], s[40:41], 0, v[208:209]
	global_load_dwordx4 v[164:167], v[246:247], off
	s_waitcnt vmcnt(0)
	v_fmamk_f32 v133, v162, 0x3a000000, v244
	v_fmamk_f32 v134, v163, 0x3a000000, v244
	v_rsq_f32_e32 v216, v133
	v_rsq_f32_e32 v214, v134
	v_fmamk_f32 v130, v130, 0x3a000000, v244
	v_fmamk_f32 v131, v131, 0x3a000000, v244
	v_rsq_f32_e32 v202, v130
	v_rsq_f32_e32 v200, v131
	v_cndmask_b32_e64 v132, 0, 1, s[0:1]
	v_mov_b32_e32 v217, v216
	v_mov_b32_e32 v215, v214
	v_pk_mul_f32 v[156:157], v[108:109], v[216:217]
	v_pk_mul_f32 v[152:153], v[100:101], v[214:215]
	v_pk_mul_f32 v[134:135], v[104:105], v[216:217]
	v_pk_mul_f32 v[130:131], v[96:97], v[214:215]
	v_cmp_ne_u32_e64 s[12:13], 1, v132
	s_and_saveexec_b64 s[0:1], s[8:9]
	s_cbranch_execz .LBB0_402
	v_mov_b32_e32 v217, v216
	v_mov_b32_e32 v215, v214
	v_pk_mul_f32 v[136:137], v[106:107], v[216:217]
	v_pk_mul_f32 v[158:159], v[110:111], v[216:217]
	v_pk_mul_f32 v[154:155], v[102:103], v[214:215]
	ds_write_b128 v232, v[134:137] offset:16
	v_pk_mul_f32 v[132:133], v[98:99], v[214:215]
	v_pk_mul_f32 v[138:139], v[46:47], v[202:203] op_sel_hi:[1,0]
	v_pk_mul_f32 v[136:137], v[44:45], v[202:203] op_sel_hi:[1,0]
	v_pk_mul_f32 v[142:143], v[38:39], v[200:201] op_sel_hi:[1,0]
	v_pk_mul_f32 v[140:141], v[36:37], v[200:201] op_sel_hi:[1,0]
	v_pk_mul_f32 v[146:147], v[42:43], v[202:203] op_sel_hi:[1,0]
	v_pk_mul_f32 v[144:145], v[40:41], v[202:203] op_sel_hi:[1,0]
	v_pk_mul_f32 v[150:151], v[34:35], v[200:201] op_sel_hi:[1,0]
	v_pk_mul_f32 v[148:149], v[32:33], v[200:201] op_sel_hi:[1,0]
	s_and_b64 vcc, exec, s[12:13]
	ds_write_b128 v232, v[156:159]
	ds_write_b128 v232, v[152:155] offset:512
	ds_write_b128 v232, v[130:133] offset:528
	ds_write_b128 v232, v[136:139] offset:2048
	ds_write_b128 v232, v[140:143] offset:2560
	ds_write_b128 v232, v[144:147] offset:2064
	ds_write_b128 v232, v[148:151] offset:2576
	s_cbranch_vccnz .LBB0_402
	s_mul_i32 s6, s52, 0xb000
	v_readlane_b32 s14, v249, 14
	s_mul_hi_i32 s7, s52, 0xb000
	s_add_u32 s6, s14, s6
	v_readlane_b32 s14, v249, 15
	v_ashrrev_i32_e32 v199, 31, v198
	s_addc_u32 s7, s14, s7
	v_lshl_add_u64 v[132:133], v[198:199], 2, s[6:7]
	global_store_dwordx4 v[132:133], v[136:139], off sc1
	s_nop 1
	s_mov_b64 s[6:7], 0x5800
	v_lshl_add_u64 v[136:137], v[132:133], 0, s[6:7]
	global_store_dwordx4 v[136:137], v[140:143], off sc1
	s_nop 1
	v_lshl_add_u64 v[136:137], v[132:133], 0, 16
	global_store_dwordx4 v[136:137], v[144:147], off sc1
	s_nop 1
	s_mov_b64 s[6:7], 0x5810
	v_lshl_add_u64 v[132:133], v[132:133], 0, s[6:7]
	global_store_dwordx4 v[132:133], v[148:151], off sc1
	s_nop 1
.LBB0_402:
	s_or_b64 exec, exec, s[0:1]
	v_ashrrev_i32_e32 v199, 31, v198
	v_readlane_b32 s36, v250, 25
	v_lshlrev_b64 v[132:133], 2, v[198:199]
	v_readlane_b32 s38, v250, 27
	v_readlane_b32 s39, v250, 28
	v_readlane_b32 s40, v250, 29
	v_readlane_b32 s41, v250, 30
	s_waitcnt lgkmcnt(0)
	s_barrier
	v_lshl_add_u64 v[204:205], s[38:39], 0, v[132:133]
	v_lshl_add_u64 v[212:213], s[96:97], 0, v[132:133]
	v_lshl_add_u64 v[206:207], s[40:41], 0, v[132:133]
	v_lshl_add_u64 v[210:211], s[94:95], 0, v[132:133]
	v_mov_b32_e32 v148, v218
	v_mov_b32_e32 v149, v219
	v_mov_b32_e32 v150, v220
	v_mov_b32_e32 v151, v221
	v_mov_b32_e32 v140, v222
	v_mov_b32_e32 v141, v223
	v_mov_b32_e32 v142, v224
	v_mov_b32_e32 v143, v225
	v_mov_b32_e32 v144, v226
	v_mov_b32_e32 v145, v227
	v_mov_b32_e32 v146, v228
	v_mov_b32_e32 v147, v229
	v_mov_b32_e32 v136, v164
	v_mov_b32_e32 v137, v165
	v_mov_b32_e32 v138, v166
	v_mov_b32_e32 v139, v167
	s_cmp_lt_i32 s52, 32
	s_cselect_b64 s[16:17], -1, 0
	s_cmp_gt_i32 s52, 31
	s_cselect_b64 s[14:15], -1, 0
	s_lshl_b32 s55, s52, 2
	s_addk_i32 s55, 0xff80
	s_add_i32 s64, s55, s86
	s_mul_hi_i32 s53, s64, 0xb000
	s_mul_i32 s64, s64, 0xb000
	s_mov_b64 s[0:1], -1
	s_and_b64 vcc, exec, s[16:17]
	v_readlane_b32 s37, v250, 26
	v_readlane_b32 s42, v250, 31
	v_readlane_b32 s43, v250, 32
	v_readlane_b32 s44, v250, 33
	v_readlane_b32 s45, v250, 34
	v_readlane_b32 s46, v250, 35
	v_readlane_b32 s47, v250, 36
	v_readlane_b32 s48, v250, 37
	v_readlane_b32 s49, v250, 38
	v_readlane_b32 s50, v250, 39
	v_readlane_b32 s51, v250, 40
	s_cbranch_vccnz .LBB0_404
	v_readlane_b32 s36, v250, 41
	v_readlane_b32 s48, v250, 53
	v_readlane_b32 s49, v250, 54
	s_mov_b64 s[68:69], s[48:49]
	s_add_u32 s0, s68, s64
	s_addc_u32 s1, s69, s53
	v_lshl_add_u64 v[132:133], v[198:199], 2, s[0:1]
	v_add_co_u32_e32 v154, vcc, 0x5000, v132
	s_mov_b64 s[0:1], 0
	s_nop 0
	v_addc_co_u32_e32 v155, vcc, 0, v133, vcc
	global_load_dwordx4 v[172:175], v[132:133], off
	global_load_dwordx4 v[168:171], v[154:155], off offset:2048
	v_readlane_b32 s37, v250, 42
	v_readlane_b32 s38, v250, 43
	v_readlane_b32 s39, v250, 44
	v_readlane_b32 s40, v250, 45
	v_readlane_b32 s41, v250, 46
	v_readlane_b32 s42, v250, 47
	v_readlane_b32 s43, v250, 48
	v_readlane_b32 s44, v250, 49
	v_readlane_b32 s45, v250, 50
	v_readlane_b32 s46, v250, 51
	v_readlane_b32 s47, v250, 52
	v_readlane_b32 s50, v250, 55
	v_readlane_b32 s51, v250, 56
	s_waitcnt vmcnt(0)
; #define PG8_LAS __attribute__((address_space(3)))
; __device__ __forceinline__ float gelu_tanh(float x) { const float u = x * (1.5957691216057308f + 0.0713548162726009f * x * x); return x * sigmoid_f(u); }
;     __device__ __forceinline__ static float dpp_up(float old, float src) { return __builtin_bit_cast(float, __builtin_amdgcn_update_dpp(__builtin_bit_cast(int, old), __builtin_bit_cast(int, src), 0x111, 0xf, 0xf, false)); }
;     __device__ __forceinline__ void operator()(const f32x4 (&acc)[2][2][4][2], const Unit& u, int wr, int wc, int fr, int fq) const {
;     ...
;                 const f32x4 w0 = *(const f32x4*)(cw + c), w1 = *(const f32x4*)(cw + DFFC + c), w2 = *(const f32x4*)(cw + 2 * DFFC + c), bb = *(const f32x4*)(cb + c);
;                 f32x4 h2, h3;
;                 if (!prompt) { h2 = *(const f32x4*)(state + ((size_t)sb * 2 + 0) * DFFC + c); h3 = *(const f32x4*)(state + ((size_t)sb * 2 + 1) * DFFC + c); }
;                 else if (blk > 0) { h2 = *(const PG8_LAS f32x4*)(xch + (((blk - 1) * 2 + 0) * 4 + wc) * 32 + 8 * fq + 4 * n); h3 = *(const PG8_LAS f32x4*)(xch + (((blk - 1) * 2 + 1) * 4 + wc) * 32 + 8 * fq + 4 * n); }
;                 else { h2 = (f32x4){0.f, 0.f, 0.f, 0.f}; h3 = h2; }
;                 const f32x4 a0 = acc[ai][0][0][n] * rs[ai][0], a1 = acc[ai][0][1][n] * rs[ai][1], a2 = acc[ai][0][2][n] * rs[ai][2], a3 = acc[ai][0][3][n] * rs[ai][3];
;                 f32x4 o0, o1, o2, o3;
; #pragma unroll
;                 for (int j = 0; j < 4; ++j) { const float p3 = dpp_up(h3[j], a3[j]), p2 = dpp_up(h2[j], a2[j]);
;                     o0[j] = gelu_tanh(bb[j] + w0[j] * p2 + w1[j] * p3 + w2[j] * a0[j]) * (acc[ai][1][0][n][j] * rs[ai][0]);
;                     o1[j] = gelu_tanh(bb[j] + w0[j] * p3 + w1[j] * a0[j] + w2[j] * a1[j]) * (acc[ai][1][1][n][j] * rs[ai][1]);
.LBB0_404:
	s_andn2_b64 vcc, exec, s[0:1]
	v_readlane_b32 s0, v249, 25
	v_readlane_b32 s1, v249, 26
	s_nop 1
	v_cndmask_b32_e64 v132, 0, 1, s[0:1]
	v_cmp_ne_u32_e64 s[0:1], 1, v132
	s_cbranch_vccnz .LBB0_407
	v_mov_b32_e32 v171, 0
	s_and_b64 vcc, exec, s[0:1]
	v_mov_b32_e32 v170, 0
	v_mov_b32_e32 v169, 0
	v_mov_b32_e32 v168, 0
	v_mov_b32_e32 v175, 0
	v_mov_b32_e32 v174, 0
	v_mov_b32_e32 v173, 0
	v_mov_b32_e32 v172, 0
	s_cbranch_vccnz .LBB0_407
	ds_read_b128 v[172:175], v235
	ds_read_b128 v[168:171], v233
.LBB0_407:
	v_fmamk_f32 v132, v160, 0x3a000000, v244
	v_rsq_f32_e32 v224, v132
	v_fmamk_f32 v132, v161, 0x3a000000, v244
	s_waitcnt lgkmcnt(1)
	v_mov_b32_dpp v172, v156 row_shr:1 row_mask:0xf bank_mask:0xf
	v_rsq_f32_e32 v222, v132
	v_mov_b32_e32 v225, v224
	s_waitcnt lgkmcnt(0)
	v_mov_b32_dpp v168, v152 row_shr:1 row_mask:0xf bank_mask:0xf
	v_fma_f32 v132, v148, v172, v136
	v_pk_mul_f32 v[164:165], v[124:125], v[224:225] op_sel_hi:[1,0]
	v_fmac_f32_e32 v132, v140, v168
	v_fmac_f32_e32 v132, v164, v144
	v_mul_f32_e32 v133, 0x3d922279, v132
	v_fmaak_f32 v133, v132, v133, 0x3fcc422a
	v_mul_f32_e32 v133, v132, v133
	v_mul_f32_e32 v133, 0xbfb8aa3b, v133
	v_exp_f32_e32 v133, v133
	v_mov_b32_e32 v223, v222
	v_pk_mul_f32 v[160:161], v[116:117], v[222:223] op_sel_hi:[1,0]
	v_mov_b32_dpp v173, v157 row_shr:1 row_mask:0xf bank_mask:0xf
	v_add_f32_e32 v133, 1.0, v133
	v_rcp_f32_e32 v133, v133
	v_mov_b32_dpp v169, v153 row_shr:1 row_mask:0xf bank_mask:0xf
	v_mov_b32_e32 v217, v216
	v_pk_mul_f32 v[158:159], v[110:111], v[216:217]
	v_mul_f32_e32 v132, v132, v133
	v_mul_f32_e32 v133, v92, v224
	v_mul_f32_e32 v132, v133, v132
	v_fma_f32 v133, v148, v168, v136
	v_fmac_f32_e32 v133, v164, v140
	v_fmac_f32_e32 v133, v160, v144
	v_mul_f32_e32 v168, 0x3d922279, v133
	v_fmaak_f32 v168, v133, v168, 0x3fcc422a
	v_mul_f32_e32 v168, v133, v168
	v_mul_f32_e32 v168, 0xbfb8aa3b, v168
	v_exp_f32_e32 v168, v168
	v_mov_b32_e32 v215, v214
	v_pk_mul_f32 v[154:155], v[102:103], v[214:215]
	v_mov_b32_dpp v174, v158 row_shr:1 row_mask:0xf bank_mask:0xf
	v_add_f32_e32 v168, 1.0, v168
	v_rcp_f32_e32 v168, v168
	v_mov_b32_dpp v170, v154 row_shr:1 row_mask:0xf bank_mask:0xf
	v_pk_mul_f32 v[166:167], v[126:127], v[224:225] op_sel_hi:[1,0]
	v_pk_mul_f32 v[162:163], v[118:119], v[222:223] op_sel_hi:[1,0]
	v_mul_f32_e32 v133, v133, v168
	v_mul_f32_e32 v168, v84, v222
	v_mul_f32_e32 v133, v168, v133
	v_fma_f32 v168, v164, v148, v136
	v_fma_f32 v136, v160, v148, v136
	v_fmac_f32_e32 v136, v156, v140
	v_fmac_f32_e32 v136, v152, v144
	v_fmac_f32_e32 v168, v160, v140
	v_mul_f32_e32 v140, 0x3d922279, v136
	v_fmaak_f32 v140, v136, v140, 0x3fcc422a
	v_mul_f32_e32 v140, v136, v140
	v_mul_f32_e32 v140, 0xbfb8aa3b, v140
	v_exp_f32_e32 v140, v140
	v_fmac_f32_e32 v168, v156, v144
	v_mov_b32_dpp v175, v159 row_shr:1 row_mask:0xf bank_mask:0xf
	v_mov_b32_dpp v171, v155 row_shr:1 row_mask:0xf bank_mask:0xf
	v_add_f32_e32 v140, 1.0, v140
	v_rcp_f32_e32 v140, v140
	v_mul_f32_e32 v172, 0x3d922279, v168
	v_fmaak_f32 v172, v168, v172, 0x3fcc422a
	v_mul_f32_e32 v172, v168, v172
	v_mul_f32_e32 v136, v136, v140
	v_mul_f32_e32 v140, v68, v214
	v_mul_f32_e32 v136, v140, v136
	v_fma_f32 v140, v149, v173, v137
	v_fmac_f32_e32 v140, v141, v169
	v_fmac_f32_e32 v140, v165, v145
	v_mul_f32_e32 v144, 0x3d922279, v140
	v_fmaak_f32 v144, v140, v144, 0x3fcc422a
	v_mul_f32_e32 v144, v140, v144
	v_mul_f32_e32 v144, 0xbfb8aa3b, v144
	v_exp_f32_e32 v144, v144
	v_mul_f32_e32 v172, 0xbfb8aa3b, v172
	v_exp_f32_e32 v172, v172
	s_and_b32 s33, s52, 15
	v_add_f32_e32 v144, 1.0, v144
	v_rcp_f32_e32 v144, v144
	v_add_f32_e32 v172, 1.0, v172
	s_cmp_lg_u32 s33, 0
	v_readlane_b32 s30, v249, 31
	v_mul_f32_e32 v140, v140, v144
	v_mul_f32_e32 v144, v93, v224
	v_mul_f32_e32 v140, v144, v140
	v_fma_f32 v144, v149, v169, v137
	v_fmac_f32_e32 v144, v165, v141
	v_fmac_f32_e32 v144, v161, v145
	v_mul_f32_e32 v148, 0x3d922279, v144
	v_fmaak_f32 v148, v144, v148, 0x3fcc422a
	v_mul_f32_e32 v148, v144, v148
	v_mul_f32_e32 v148, 0xbfb8aa3b, v148
	v_exp_f32_e32 v148, v148
	v_rcp_f32_e32 v172, v172
	s_cselect_b64 s[6:7], -1, 0
	v_readlane_b32 s31, v249, 32
	v_add_f32_e32 v148, 1.0, v148
	v_rcp_f32_e32 v148, v148
	s_and_b64 s[6:7], s[30:31], s[6:7]
	s_and_b64 s[6:7], s[16:17], s[6:7]
	s_mul_hi_i32 s65, s52, 0x16000
	v_mul_f32_e32 v144, v144, v148
	v_mul_f32_e32 v148, v85, v222
	v_mul_f32_e32 v144, v148, v144
	v_fma_f32 v148, v165, v149, v137
	v_fma_f32 v137, v161, v149, v137
	v_fmac_f32_e32 v137, v157, v141
	v_fmac_f32_e32 v137, v153, v145
	v_fmac_f32_e32 v148, v161, v141
	v_mul_f32_e32 v141, 0x3d922279, v137
	v_fmaak_f32 v141, v137, v141, 0x3fcc422a
	v_mul_f32_e32 v141, v137, v141
	v_mul_f32_e32 v141, 0xbfb8aa3b, v141
	v_exp_f32_e32 v141, v141
	v_fmac_f32_e32 v148, v157, v145
	v_mul_f32_e32 v169, 0x3d922279, v148
	v_fmaak_f32 v169, v148, v169, 0x3fcc422a
	v_add_f32_e32 v141, 1.0, v141
	v_rcp_f32_e32 v141, v141
	v_mul_f32_e32 v169, v148, v169
	v_mul_f32_e32 v169, 0xbfb8aa3b, v169
	v_exp_f32_e32 v169, v169
	v_mul_f32_e32 v137, v137, v141
	v_mul_f32_e32 v141, v69, v214
	v_mul_f32_e32 v137, v141, v137
; __device__ __forceinline__ unsigned cvt_pk_bf16(float lo, float hi) { unsigned r; asm volatile("v_cvt_pk_bf16_f32 %0, %1, %2" : "=v"(r) : "v"(lo), "v"(hi)); return r; }
; __device__ __forceinline__ void st16_wt(void* p, f32x4 v) { asm volatile("global_store_dwordx4 %0, %1, off sc1\n\ts_nop 1" :: "v"(p), "v"(v) : "memory"); }
; __device__ __forceinline__ float gelu_tanh(float x) { const float u = x * (1.5957691216057308f + 0.0713548162726009f * x * x); return x * sigmoid_f(u); }
;     __device__ __forceinline__ static float dpp_up(float old, float src) { return __builtin_bit_cast(float, __builtin_amdgcn_update_dpp(__builtin_bit_cast(int, old), __builtin_bit_cast(int, src), 0x111, 0xf, 0xf, false)); }
;     __device__ __forceinline__ void operator()(const f32x4 (&acc)[2][2][4][2], const Unit& u, int wr, int wc, int fr, int fq) const {
;     ...
;                 for (int j = 0; j < 4; ++j) { const float p3 = dpp_up(h3[j], a3[j]), p2 = dpp_up(h2[j], a2[j]);
;                     o0[j] = gelu_tanh(bb[j] + w0[j] * p2 + w1[j] * p3 + w2[j] * a0[j]) * (acc[ai][1][0][n][j] * rs[ai][0]);
;                     o1[j] = gelu_tanh(bb[j] + w0[j] * p3 + w1[j] * a0[j] + w2[j] * a1[j]) * (acc[ai][1][1][n][j] * rs[ai][1]);
;                     o2[j] = gelu_tanh(bb[j] + w0[j] * a0[j] + w1[j] * a1[j] + w2[j] * a2[j]) * (acc[ai][1][2][n][j] * rs[ai][2]);
;                     o3[j] = gelu_tanh(bb[j] + w0[j] * a1[j] + w1[j] * a2[j] + w2[j] * a3[j]) * (acc[ai][1][3][n][j] * rs[ai][3]); }
;                 pk[0][n].x = cvt_pk_bf16(o0[0], o0[1]); pk[0][n].y = cvt_pk_bf16(o0[2], o0[3]); pk[1][n].x = cvt_pk_bf16(o1[0], o1[1]); pk[1][n].y = cvt_pk_bf16(o1[2], o1[3]);
;                 pk[2][n].x = cvt_pk_bf16(o2[0], o2[1]); pk[2][n].y = cvt_pk_bf16(o2[2], o2[3]); pk[3][n].x = cvt_pk_bf16(o3[0], o3[1]); pk[3][n].y = cvt_pk_bf16(o3[2], o3[3]);
;                 if (pend && fr == 0) {
;                     st16_wt(PEND + (((size_t)u.pm * 2 + 0) * 2 + 0) * DFFC + c, a0); st16_wt(PEND + (((size_t)u.pm * 2 + 0) * 2 + 1) * DFFC + c, acc[ai][1][0][n] * rs[ai][0]);
;                     st16_wt(PEND + (((size_t)u.pm * 2 + 1) * 2 + 0) * DFFC + c, a1); st16_wt(PEND + (((size_t)u.pm * 2 + 1) * 2 + 1) * DFFC + c, acc[ai][1][1][n] * rs[ai][1]); }
	v_fma_f32 v141, v150, v174, v138
	v_fmac_f32_e32 v141, v142, v170
	v_fmac_f32_e32 v141, v166, v146
	v_mul_f32_e32 v145, 0x3d922279, v141
	v_fmaak_f32 v145, v141, v145, 0x3fcc422a
	v_mul_f32_e32 v145, v141, v145
	v_mul_f32_e32 v145, 0xbfb8aa3b, v145
	v_exp_f32_e32 v145, v145
	v_add_f32_e32 v169, 1.0, v169
	v_rcp_f32_e32 v169, v169
	s_mul_i32 s68, s52, 0x16000
	v_add_f32_e32 v145, 1.0, v145
	v_rcp_f32_e32 v145, v145
	v_mul_f32_e32 v148, v148, v169
	v_mul_f32_e32 v169, v77, v216
	v_mul_f32_e32 v148, v169, v148
	v_mul_f32_e32 v141, v141, v145
	v_mul_f32_e32 v145, v94, v224
	v_mul_f32_e32 v141, v145, v141
	v_fma_f32 v145, v150, v170, v138
	v_fmac_f32_e32 v145, v166, v142
	v_fmac_f32_e32 v145, v162, v146
	v_mul_f32_e32 v149, 0x3d922279, v145
	v_fmaak_f32 v149, v145, v149, 0x3fcc422a
	v_mul_f32_e32 v149, v145, v149
	v_mul_f32_e32 v149, 0xbfb8aa3b, v149
	v_exp_f32_e32 v149, v149
	s_and_b64 s[30:31], s[84:85], s[6:7]
	v_mul_f32_e32 v168, v168, v172
	v_mul_f32_e32 v172, v76, v216
	v_add_f32_e32 v149, 1.0, v149
	v_rcp_f32_e32 v149, v149
	v_mul_f32_e32 v168, v172, v168
	v_mul_f32_e32 v145, v145, v149
	v_mul_f32_e32 v149, v86, v222
	v_mul_f32_e32 v145, v149, v145
	v_fma_f32 v149, v166, v150, v138
	v_fma_f32 v138, v162, v150, v138
	v_fmac_f32_e32 v149, v162, v142
	v_fmac_f32_e32 v138, v158, v142
	v_fmac_f32_e32 v149, v158, v146
	v_fmac_f32_e32 v138, v154, v146
	v_mul_f32_e32 v169, 0x3d922279, v149
	v_mul_f32_e32 v142, 0x3d922279, v138
	v_fmaak_f32 v169, v149, v169, 0x3fcc422a
	v_fmaak_f32 v142, v138, v142, 0x3fcc422a
	v_mul_f32_e32 v169, v149, v169
	v_mul_f32_e32 v142, v138, v142
	v_mul_f32_e32 v169, 0xbfb8aa3b, v169
	v_mul_f32_e32 v142, 0xbfb8aa3b, v142
	v_exp_f32_e32 v169, v169
	v_exp_f32_e32 v142, v142
	v_add_f32_e32 v169, 1.0, v169
	v_add_f32_e32 v142, 1.0, v142
	v_rcp_f32_e32 v169, v169
	v_rcp_f32_e32 v142, v142
	v_mul_f32_e32 v149, v149, v169
	v_mul_f32_e32 v169, v78, v216
	v_mul_f32_e32 v138, v138, v142
	v_mul_f32_e32 v142, v70, v214
	v_mul_f32_e32 v149, v169, v149
	v_mul_f32_e32 v169, v142, v138
	v_fma_f32 v138, v151, v175, v139
	v_fmac_f32_e32 v138, v143, v171
	v_fmac_f32_e32 v138, v167, v147
	v_mul_f32_e32 v142, 0x3d922279, v138
	v_fmaak_f32 v142, v138, v142, 0x3fcc422a
	v_mul_f32_e32 v142, v138, v142
	v_mul_f32_e32 v142, 0xbfb8aa3b, v142
	v_exp_f32_e32 v142, v142
	s_nop 0
	v_add_f32_e32 v142, 1.0, v142
	v_rcp_f32_e32 v142, v142
	s_nop 0
	v_mul_f32_e32 v138, v138, v142
	v_mul_f32_e32 v142, v95, v224
	v_mul_f32_e32 v138, v142, v138
	v_fma_f32 v142, v151, v171, v139
	v_fmac_f32_e32 v142, v167, v143
	v_fmac_f32_e32 v142, v163, v147
	v_mul_f32_e32 v146, 0x3d922279, v142
	v_fmaak_f32 v146, v142, v146, 0x3fcc422a
	v_mul_f32_e32 v146, v142, v146
	v_mul_f32_e32 v146, 0xbfb8aa3b, v146
	v_exp_f32_e32 v146, v146
	s_nop 0
	v_add_f32_e32 v146, 1.0, v146
	v_rcp_f32_e32 v146, v146
	s_nop 0
	v_mul_f32_e32 v142, v142, v146
	v_mul_f32_e32 v146, v87, v222
	v_mul_f32_e32 v142, v146, v142
	v_fma_f32 v146, v167, v151, v139
	v_fmac_f32_e32 v139, v163, v151
	v_fmac_f32_e32 v139, v159, v143
	v_fmac_f32_e32 v146, v163, v143
	v_fmac_f32_e32 v139, v155, v147
	v_fmac_f32_e32 v146, v159, v147
	v_mul_f32_e32 v143, 0x3d922279, v139
	v_mul_f32_e32 v150, 0x3d922279, v146
	v_fmaak_f32 v143, v139, v143, 0x3fcc422a
	v_fmaak_f32 v150, v146, v150, 0x3fcc422a
	v_mul_f32_e32 v143, v139, v143
	v_mul_f32_e32 v150, v146, v150
	v_mul_f32_e32 v143, 0xbfb8aa3b, v143
	v_mul_f32_e32 v150, 0xbfb8aa3b, v150
	v_exp_f32_e32 v143, v143
	v_exp_f32_e32 v150, v150
	v_add_f32_e32 v143, 1.0, v143
	v_add_f32_e32 v150, 1.0, v150
	v_rcp_f32_e32 v143, v143
	v_rcp_f32_e32 v150, v150
	v_mul_f32_e32 v139, v139, v143
	v_mul_f32_e32 v143, v71, v214
	v_mul_f32_e32 v146, v146, v150
	v_mul_f32_e32 v150, v79, v216
	v_mul_f32_e32 v139, v143, v139
	v_mul_f32_e32 v170, v150, v146
	v_cvt_pk_bf16_f32 v150, v132, v140
	v_cvt_pk_bf16_f32 v151, v141, v138
	v_cvt_pk_bf16_f32 v146, v133, v144
	v_cvt_pk_bf16_f32 v147, v145, v142
	v_cvt_pk_bf16_f32 v142, v168, v148
	v_cvt_pk_bf16_f32 v143, v149, v170
	v_cvt_pk_bf16_f32 v138, v136, v137
	v_cvt_pk_bf16_f32 v139, v169, v139
	s_and_saveexec_b64 s[6:7], s[30:31]
	s_cbranch_execz .LBB0_409
	v_readlane_b32 s16, v249, 9
	s_add_u32 s16, s16, s68
	v_readlane_b32 s17, v249, 11
	s_addc_u32 s17, s17, s65
	v_mov_b32_e32 v140, v224
	v_lshl_add_u64 v[132:133], v[198:199], 2, s[16:17]
	s_mov_b64 s[16:17], 0x5800
	global_store_dwordx4 v[132:133], v[164:167], off sc1
	s_nop 1
	v_lshl_add_u64 v[136:137], v[132:133], 0, s[16:17]
	v_mov_b32_e32 v141, v224
	s_mov_b64 s[16:17], 0xb000
	v_pk_mul_f32 v[166:167], v[94:95], v[140:141]
	v_pk_mul_f32 v[164:165], v[92:93], v[224:225]
	s_nop 0
	global_store_dwordx4 v[136:137], v[164:167], off sc1
	s_nop 1
	v_lshl_add_u64 v[136:137], v[132:133], 0, s[16:17]
	global_store_dwordx4 v[136:137], v[160:163], off sc1
	s_nop 1
	s_mov_b64 s[16:17], 0x10800
	v_mov_b32_e32 v136, v222
	v_mov_b32_e32 v137, v222
	v_lshl_add_u64 v[132:133], v[132:133], 0, s[16:17]
	v_pk_mul_f32 v[162:163], v[86:87], v[136:137]
	v_pk_mul_f32 v[160:161], v[84:85], v[222:223]
	s_nop 0
	global_store_dwordx4 v[132:133], v[160:163], off sc1
	s_nop 1
